# same as the two-body version with the rarely taken softmax fallback (score recompute) re-reading its V fragments from the transposed image (fallback verified by forcing it on odd and on even tiles)
# speedup vs baseline: 1.0009x; 1.0009x over previous
.Lat_redo_a:
	s_mov_b32 s84, 1
	s_waitcnt lgkmcnt(0)
	v_mov_b32_e32 v234, v221
	v_xor_b32_e32 v235, 64, v234
	v_xor_b32_e32 v236, 0x80, v234
	v_xor_b32_e32 v237, 0xc0, v234
	ds_read_b128 v[162:165], v234
	s_waitcnt lgkmcnt(0)
	v_mfma_f32_16x16x32_bf16 v[130:133], v[162:165], v[178:181], v[246:249]
	v_mfma_f32_16x16x32_bf16 v[146:149], v[162:165], v[194:197], v[250:253]
	ds_read_b128 v[162:165], v235
	s_waitcnt lgkmcnt(0)
	v_mfma_f32_16x16x32_bf16 v[130:133], v[162:165], v[182:185], v[130:133]
	v_mfma_f32_16x16x32_bf16 v[146:149], v[162:165], v[198:201], v[146:149]
	ds_read_b128 v[162:165], v236
	s_waitcnt lgkmcnt(0)
	v_mfma_f32_16x16x32_bf16 v[130:133], v[162:165], v[186:189], v[130:133]
	v_mfma_f32_16x16x32_bf16 v[146:149], v[162:165], v[202:205], v[146:149]
	ds_read_b128 v[162:165], v237
	s_waitcnt lgkmcnt(0)
	v_mfma_f32_16x16x32_bf16 v[130:133], v[162:165], v[190:193], v[130:133]
	v_mfma_f32_16x16x32_bf16 v[146:149], v[162:165], v[206:209], v[146:149]
	ds_read_b128 v[162:165], v234 offset:4096
	s_waitcnt lgkmcnt(0)
	v_mfma_f32_16x16x32_bf16 v[134:137], v[162:165], v[178:181], v[246:249]
	v_mfma_f32_16x16x32_bf16 v[150:153], v[162:165], v[194:197], v[250:253]
	ds_read_b128 v[162:165], v235 offset:4096
	s_waitcnt lgkmcnt(0)
	v_mfma_f32_16x16x32_bf16 v[134:137], v[162:165], v[182:185], v[134:137]
	v_mfma_f32_16x16x32_bf16 v[150:153], v[162:165], v[198:201], v[150:153]
	ds_read_b128 v[162:165], v236 offset:4096
	s_waitcnt lgkmcnt(0)
	v_mfma_f32_16x16x32_bf16 v[134:137], v[162:165], v[186:189], v[134:137]
	v_mfma_f32_16x16x32_bf16 v[150:153], v[162:165], v[202:205], v[150:153]
	ds_read_b128 v[162:165], v237 offset:4096
	s_waitcnt lgkmcnt(0)
	v_mfma_f32_16x16x32_bf16 v[134:137], v[162:165], v[190:193], v[134:137]
	v_mfma_f32_16x16x32_bf16 v[150:153], v[162:165], v[206:209], v[150:153]
	ds_read_b128 v[162:165], v234 offset:8192
	s_waitcnt lgkmcnt(0)
	v_mfma_f32_16x16x32_bf16 v[138:141], v[162:165], v[178:181], v[246:249]
	v_mfma_f32_16x16x32_bf16 v[154:157], v[162:165], v[194:197], v[250:253]
	ds_read_b128 v[162:165], v235 offset:8192
	s_waitcnt lgkmcnt(0)
	v_mfma_f32_16x16x32_bf16 v[138:141], v[162:165], v[182:185], v[138:141]
	v_mfma_f32_16x16x32_bf16 v[154:157], v[162:165], v[198:201], v[154:157]
	ds_read_b128 v[162:165], v236 offset:8192
	s_waitcnt lgkmcnt(0)
	v_mfma_f32_16x16x32_bf16 v[138:141], v[162:165], v[186:189], v[138:141]
	v_mfma_f32_16x16x32_bf16 v[154:157], v[162:165], v[202:205], v[154:157]
	ds_read_b128 v[162:165], v237 offset:8192
	s_waitcnt lgkmcnt(0)
	v_mfma_f32_16x16x32_bf16 v[138:141], v[162:165], v[190:193], v[138:141]
	v_mfma_f32_16x16x32_bf16 v[154:157], v[162:165], v[206:209], v[154:157]
	ds_read_b128 v[162:165], v234 offset:12288
	s_waitcnt lgkmcnt(0)
	v_mfma_f32_16x16x32_bf16 v[142:145], v[162:165], v[178:181], v[246:249]
	v_mfma_f32_16x16x32_bf16 v[158:161], v[162:165], v[194:197], v[250:253]
	ds_read_b128 v[162:165], v235 offset:12288
	s_waitcnt lgkmcnt(0)
	v_mfma_f32_16x16x32_bf16 v[142:145], v[162:165], v[182:185], v[142:145]
	v_mfma_f32_16x16x32_bf16 v[158:161], v[162:165], v[198:201], v[158:161]
	ds_read_b128 v[162:165], v236 offset:12288
	s_waitcnt lgkmcnt(0)
	v_mfma_f32_16x16x32_bf16 v[142:145], v[162:165], v[186:189], v[142:145]
	v_mfma_f32_16x16x32_bf16 v[158:161], v[162:165], v[202:205], v[158:161]
	ds_read_b128 v[162:165], v237 offset:12288
	s_waitcnt lgkmcnt(0)
	v_mfma_f32_16x16x32_bf16 v[142:145], v[162:165], v[190:193], v[142:145]
	v_mfma_f32_16x16x32_bf16 v[158:161], v[162:165], v[206:209], v[158:161]
	ds_read_b128 v[162:165], v242
	ds_read_b128 v[166:169], v243
	ds_read_b128 v[170:173], v242 offset:2048
	ds_read_b128 v[174:177], v243 offset:2048
	s_nop 7
	s_branch .Lat_dt_a

.Lat_redo_c:
	s_mov_b32 s84, 1
	s_waitcnt lgkmcnt(0)
	v_mov_b32_e32 v234, v221
	v_xor_b32_e32 v235, 64, v234
	v_xor_b32_e32 v236, 0x80, v234
	v_xor_b32_e32 v237, 0xc0, v234
	ds_read_b128 v[162:165], v234 offset:32768
	s_waitcnt lgkmcnt(0)
	v_mfma_f32_16x16x32_bf16 v[130:133], v[162:165], v[178:181], v[246:249]
	v_mfma_f32_16x16x32_bf16 v[146:149], v[162:165], v[194:197], v[250:253]
	ds_read_b128 v[162:165], v235 offset:32768
	s_waitcnt lgkmcnt(0)
	v_mfma_f32_16x16x32_bf16 v[130:133], v[162:165], v[182:185], v[130:133]
	v_mfma_f32_16x16x32_bf16 v[146:149], v[162:165], v[198:201], v[146:149]
	ds_read_b128 v[162:165], v236 offset:32768
	s_waitcnt lgkmcnt(0)
	v_mfma_f32_16x16x32_bf16 v[130:133], v[162:165], v[186:189], v[130:133]
	v_mfma_f32_16x16x32_bf16 v[146:149], v[162:165], v[202:205], v[146:149]
	ds_read_b128 v[162:165], v237 offset:32768
	s_waitcnt lgkmcnt(0)
	v_mfma_f32_16x16x32_bf16 v[130:133], v[162:165], v[190:193], v[130:133]
	v_mfma_f32_16x16x32_bf16 v[146:149], v[162:165], v[206:209], v[146:149]
	ds_read_b128 v[162:165], v234 offset:36864
	s_waitcnt lgkmcnt(0)
	v_mfma_f32_16x16x32_bf16 v[134:137], v[162:165], v[178:181], v[246:249]
	v_mfma_f32_16x16x32_bf16 v[150:153], v[162:165], v[194:197], v[250:253]
	ds_read_b128 v[162:165], v235 offset:36864
	s_waitcnt lgkmcnt(0)
	v_mfma_f32_16x16x32_bf16 v[134:137], v[162:165], v[182:185], v[134:137]
	v_mfma_f32_16x16x32_bf16 v[150:153], v[162:165], v[198:201], v[150:153]
	ds_read_b128 v[162:165], v236 offset:36864
	s_waitcnt lgkmcnt(0)
	v_mfma_f32_16x16x32_bf16 v[134:137], v[162:165], v[186:189], v[134:137]
	v_mfma_f32_16x16x32_bf16 v[150:153], v[162:165], v[202:205], v[150:153]
	ds_read_b128 v[162:165], v237 offset:36864
	s_waitcnt lgkmcnt(0)
	v_mfma_f32_16x16x32_bf16 v[134:137], v[162:165], v[190:193], v[134:137]
	v_mfma_f32_16x16x32_bf16 v[150:153], v[162:165], v[206:209], v[150:153]
	ds_read_b128 v[162:165], v234 offset:40960
	s_waitcnt lgkmcnt(0)
	v_mfma_f32_16x16x32_bf16 v[138:141], v[162:165], v[178:181], v[246:249]
	v_mfma_f32_16x16x32_bf16 v[154:157], v[162:165], v[194:197], v[250:253]
	ds_read_b128 v[162:165], v235 offset:40960
	s_waitcnt lgkmcnt(0)
	v_mfma_f32_16x16x32_bf16 v[138:141], v[162:165], v[182:185], v[138:141]
	v_mfma_f32_16x16x32_bf16 v[154:157], v[162:165], v[198:201], v[154:157]
	ds_read_b128 v[162:165], v236 offset:40960
	s_waitcnt lgkmcnt(0)
	v_mfma_f32_16x16x32_bf16 v[138:141], v[162:165], v[186:189], v[138:141]
	v_mfma_f32_16x16x32_bf16 v[154:157], v[162:165], v[202:205], v[154:157]
	ds_read_b128 v[162:165], v237 offset:40960
	s_waitcnt lgkmcnt(0)
	v_mfma_f32_16x16x32_bf16 v[138:141], v[162:165], v[190:193], v[138:141]
	v_mfma_f32_16x16x32_bf16 v[154:157], v[162:165], v[206:209], v[154:157]
	ds_read_b128 v[162:165], v234 offset:45056
	s_waitcnt lgkmcnt(0)
	v_mfma_f32_16x16x32_bf16 v[142:145], v[162:165], v[178:181], v[246:249]
	v_mfma_f32_16x16x32_bf16 v[158:161], v[162:165], v[194:197], v[250:253]
	ds_read_b128 v[162:165], v235 offset:45056
	s_waitcnt lgkmcnt(0)
	v_mfma_f32_16x16x32_bf16 v[142:145], v[162:165], v[182:185], v[142:145]
	v_mfma_f32_16x16x32_bf16 v[158:161], v[162:165], v[198:201], v[158:161]
	ds_read_b128 v[162:165], v236 offset:45056
	s_waitcnt lgkmcnt(0)
	v_mfma_f32_16x16x32_bf16 v[142:145], v[162:165], v[186:189], v[142:145]
	v_mfma_f32_16x16x32_bf16 v[158:161], v[162:165], v[202:205], v[158:161]
	ds_read_b128 v[162:165], v237 offset:45056
	s_waitcnt lgkmcnt(0)
	v_mfma_f32_16x16x32_bf16 v[142:145], v[162:165], v[190:193], v[142:145]
	v_mfma_f32_16x16x32_bf16 v[158:161], v[162:165], v[206:209], v[158:161]
	ds_read_b128 v[162:165], v242 offset:32768
	ds_read_b128 v[166:169], v243 offset:32768
	ds_read_b128 v[170:173], v242 offset:34816
	ds_read_b128 v[174:177], v243 offset:34816
	s_nop 7
	s_branch .Lat_dt_c
